# P5 SwiGLU epilogue rewritten: row-scale partials loaded once per row (2 rows/lane, 8 loads up front before the closing barrier), ds_bpermute distribution, 8 groups back-to-back without per-group vmcnt
# speedup vs baseline: 1.0102x; 1.0102x over previous
.LBB0_922:
	v_lshl_add_u32 v148, s59, 8, v150
	v_lshrrev_b32_e32 v144, 4, v184
	v_lshl_add_u32 v145, v144, 4, v148
	v_lshlrev_b32_e32 v146, 6, v145
	v_add_u32_e32 v147, 0x2000, v146
	global_load_dwordx4 v[186:189], v146, s[14:15] offset:0
	global_load_dwordx4 v[190:193], v146, s[14:15] offset:16
	global_load_dwordx4 v[194:197], v146, s[14:15] offset:32
	global_load_dwordx4 v[198:201], v146, s[14:15] offset:48
	global_load_dwordx4 v[202:205], v147, s[14:15] offset:0
	global_load_dwordx4 v[206:209], v147, s[14:15] offset:16
	global_load_dwordx4 v[210:213], v147, s[14:15] offset:32
	global_load_dwordx4 v[214:217], v147, s[14:15] offset:48
	s_and_b64 vcc, exec, s[94:95]
	s_cbranch_vccz .LBB0_924
	s_barrier
.LBB0_924:
	v_and_b32_e32 v157, 15, v184
	v_lshlrev_b32_e32 v157, 2, v157
	v_mov_b32_e32 v160, v157
	v_add_u32_e32 v161, 64, v157
	v_add_u32_e32 v162, 128, v157
	v_add_u32_e32 v163, 192, v157
	s_and_b64 vcc, exec, s[4:5]
	s_waitcnt vmcnt(0)
	v_add_f32_e32 v186, v186, v187
	v_add_f32_e32 v188, v188, v189
	v_add_f32_e32 v190, v190, v191
	v_add_f32_e32 v192, v192, v193
	v_add_f32_e32 v194, v194, v195
	v_add_f32_e32 v196, v196, v197
	v_add_f32_e32 v198, v198, v199
	v_add_f32_e32 v200, v200, v201
	v_add_f32_e32 v186, v186, v188
	v_add_f32_e32 v190, v190, v192
	v_add_f32_e32 v194, v194, v196
	v_add_f32_e32 v198, v198, v200
	v_add_f32_e32 v158, v186, v190
	v_add_f32_e32 v158, v158, v194
	v_add_f32_e32 v158, v158, v198
	v_fmamk_f32 v158, v158, 0x3a800000, v156
	v_add_f32_e32 v202, v202, v203
	v_add_f32_e32 v204, v204, v205
	v_add_f32_e32 v206, v206, v207
	v_add_f32_e32 v208, v208, v209
	v_add_f32_e32 v210, v210, v211
	v_add_f32_e32 v212, v212, v213
	v_add_f32_e32 v214, v214, v215
	v_add_f32_e32 v216, v216, v217
	v_add_f32_e32 v202, v202, v204
	v_add_f32_e32 v206, v206, v208
	v_add_f32_e32 v210, v210, v212
	v_add_f32_e32 v214, v214, v216
	v_add_f32_e32 v159, v202, v206
	v_add_f32_e32 v159, v159, v210
	v_add_f32_e32 v159, v159, v214
	v_fmamk_f32 v159, v159, 0x3a800000, v156
	v_rsq_f32_e32 v158, v158
	v_rsq_f32_e32 v159, v159
	v_lshl_add_u32 v203, s60, 7, v152
	v_lshlrev_b32_e32 v203, 1, v203
	v_mad_u32_u24 v202, v148, s52, v203
	ds_bpermute_b32 v164, v160, v158
	ds_bpermute_b32 v166, v161, v158
	ds_bpermute_b32 v168, v162, v158
	ds_bpermute_b32 v170, v163, v158
	ds_bpermute_b32 v172, v160, v159
	ds_bpermute_b32 v174, v161, v159
	ds_bpermute_b32 v176, v162, v159
	ds_bpermute_b32 v178, v163, v159
	v_mov_b32_e32 v204, v202
	v_add_u32_e32 v205, 0x16000, v202
	v_add_u32_e32 v206, 0x2c000, v202
	v_add_u32_e32 v207, 0x42000, v202
	v_add_u32_e32 v208, 0xb0000, v202
	v_add_u32_e32 v209, 0xc6000, v202
	v_add_u32_e32 v210, 0xdc000, v202
	v_add_u32_e32 v211, 0xf2000, v202
	s_waitcnt lgkmcnt(7)
	v_pk_mul_f32 v[120:121], v[120:121], v[164:165] op_sel_hi:[1,0]
	v_pk_mul_f32 v[122:123], v[122:123], v[164:165] op_sel_hi:[1,0]
	v_pk_mul_f32 v[116:117], v[116:117], v[164:165] op_sel_hi:[1,0]
	v_pk_mul_f32 v[118:119], v[118:119], v[164:165] op_sel_hi:[1,0]
	v_pk_mul_f32 v[124:125], v[124:125], v[164:165] op_sel_hi:[1,0]
	v_pk_mul_f32 v[126:127], v[126:127], v[164:165] op_sel_hi:[1,0]
	v_pk_mul_f32 v[112:113], v[112:113], v[164:165] op_sel_hi:[1,0]
	v_pk_mul_f32 v[114:115], v[114:115], v[164:165] op_sel_hi:[1,0]
	v_mul_f32_e32 v186, 0xbfb8aa3b, v120
	v_mul_f32_e32 v187, 0xbfb8aa3b, v121
	v_mul_f32_e32 v188, 0xbfb8aa3b, v122
	v_mul_f32_e32 v189, 0xbfb8aa3b, v123
	v_mul_f32_e32 v190, 0xbfb8aa3b, v116
	v_mul_f32_e32 v191, 0xbfb8aa3b, v117
	v_mul_f32_e32 v192, 0xbfb8aa3b, v118
	v_mul_f32_e32 v193, 0xbfb8aa3b, v119
	v_exp_f32_e32 v186, v186
	v_exp_f32_e32 v187, v187
	v_exp_f32_e32 v188, v188
	v_exp_f32_e32 v189, v189
	v_exp_f32_e32 v190, v190
	v_exp_f32_e32 v191, v191
	v_exp_f32_e32 v192, v192
	v_exp_f32_e32 v193, v193
	v_add_f32_e32 v186, 1.0, v186
	v_add_f32_e32 v187, 1.0, v187
	v_add_f32_e32 v188, 1.0, v188
	v_add_f32_e32 v189, 1.0, v189
	v_add_f32_e32 v190, 1.0, v190
	v_add_f32_e32 v191, 1.0, v191
	v_add_f32_e32 v192, 1.0, v192
	v_add_f32_e32 v193, 1.0, v193
	v_rcp_f32_e32 v186, v186
	v_rcp_f32_e32 v187, v187
	v_rcp_f32_e32 v188, v188
	v_rcp_f32_e32 v189, v189
	v_rcp_f32_e32 v190, v190
	v_rcp_f32_e32 v191, v191
	v_rcp_f32_e32 v192, v192
	v_rcp_f32_e32 v193, v193
	v_pk_mul_f32 v[120:121], v[120:121], v[186:187]
	v_pk_mul_f32 v[122:123], v[122:123], v[188:189]
	v_pk_mul_f32 v[116:117], v[116:117], v[190:191]
	v_pk_mul_f32 v[118:119], v[118:119], v[192:193]
	v_pk_mul_f32 v[120:121], v[124:125], v[120:121]
	v_pk_mul_f32 v[122:123], v[126:127], v[122:123]
	v_pk_mul_f32 v[116:117], v[112:113], v[116:117]
	v_pk_mul_f32 v[118:119], v[114:115], v[118:119]
	v_cvt_pk_bf16_f32 v112, v120, v121
	v_cvt_pk_bf16_f32 v113, v122, v123
	v_cvt_pk_bf16_f32 v114, v116, v117
	v_cvt_pk_bf16_f32 v115, v118, v119
	global_store_dwordx4 v204, v[112:115], s[82:83]
	s_waitcnt lgkmcnt(6)
	v_pk_mul_f32 v[108:109], v[108:109], v[166:167] op_sel_hi:[1,0]
	v_pk_mul_f32 v[110:111], v[110:111], v[166:167] op_sel_hi:[1,0]
	v_pk_mul_f32 v[100:101], v[100:101], v[166:167] op_sel_hi:[1,0]
	v_pk_mul_f32 v[102:103], v[102:103], v[166:167] op_sel_hi:[1,0]
	v_pk_mul_f32 v[104:105], v[104:105], v[166:167] op_sel_hi:[1,0]
	v_pk_mul_f32 v[106:107], v[106:107], v[166:167] op_sel_hi:[1,0]
	v_pk_mul_f32 v[96:97], v[96:97], v[166:167] op_sel_hi:[1,0]
	v_pk_mul_f32 v[98:99], v[98:99], v[166:167] op_sel_hi:[1,0]
	v_mul_f32_e32 v194, 0xbfb8aa3b, v108
	v_mul_f32_e32 v195, 0xbfb8aa3b, v109
	v_mul_f32_e32 v196, 0xbfb8aa3b, v110
	v_mul_f32_e32 v197, 0xbfb8aa3b, v111
	v_mul_f32_e32 v198, 0xbfb8aa3b, v100
	v_mul_f32_e32 v199, 0xbfb8aa3b, v101
	v_mul_f32_e32 v200, 0xbfb8aa3b, v102
	v_mul_f32_e32 v201, 0xbfb8aa3b, v103
	v_exp_f32_e32 v194, v194
	v_exp_f32_e32 v195, v195
	v_exp_f32_e32 v196, v196
	v_exp_f32_e32 v197, v197
	v_exp_f32_e32 v198, v198
	v_exp_f32_e32 v199, v199
	v_exp_f32_e32 v200, v200
	v_exp_f32_e32 v201, v201
	v_add_f32_e32 v194, 1.0, v194
	v_add_f32_e32 v195, 1.0, v195
	v_add_f32_e32 v196, 1.0, v196
	v_add_f32_e32 v197, 1.0, v197
	v_add_f32_e32 v198, 1.0, v198
	v_add_f32_e32 v199, 1.0, v199
	v_add_f32_e32 v200, 1.0, v200
	v_add_f32_e32 v201, 1.0, v201
	v_rcp_f32_e32 v194, v194
	v_rcp_f32_e32 v195, v195
	v_rcp_f32_e32 v196, v196
	v_rcp_f32_e32 v197, v197
	v_rcp_f32_e32 v198, v198
	v_rcp_f32_e32 v199, v199
	v_rcp_f32_e32 v200, v200
	v_rcp_f32_e32 v201, v201
	v_pk_mul_f32 v[108:109], v[108:109], v[194:195]
	v_pk_mul_f32 v[110:111], v[110:111], v[196:197]
	v_pk_mul_f32 v[100:101], v[100:101], v[198:199]
	v_pk_mul_f32 v[102:103], v[102:103], v[200:201]
	v_pk_mul_f32 v[108:109], v[104:105], v[108:109]
	v_pk_mul_f32 v[110:111], v[106:107], v[110:111]
	v_pk_mul_f32 v[100:101], v[96:97], v[100:101]
	v_pk_mul_f32 v[102:103], v[98:99], v[102:103]
	v_cvt_pk_bf16_f32 v96, v108, v109
	v_cvt_pk_bf16_f32 v97, v110, v111
	v_cvt_pk_bf16_f32 v98, v100, v101
	v_cvt_pk_bf16_f32 v99, v102, v103
	global_store_dwordx4 v205, v[96:99], s[82:83]
	s_waitcnt lgkmcnt(5)
	v_pk_mul_f32 v[92:93], v[92:93], v[168:169] op_sel_hi:[1,0]
	v_pk_mul_f32 v[94:95], v[94:95], v[168:169] op_sel_hi:[1,0]
	v_pk_mul_f32 v[84:85], v[84:85], v[168:169] op_sel_hi:[1,0]
	v_pk_mul_f32 v[86:87], v[86:87], v[168:169] op_sel_hi:[1,0]
	v_pk_mul_f32 v[88:89], v[88:89], v[168:169] op_sel_hi:[1,0]
	v_pk_mul_f32 v[90:91], v[90:91], v[168:169] op_sel_hi:[1,0]
	v_pk_mul_f32 v[80:81], v[80:81], v[168:169] op_sel_hi:[1,0]
	v_pk_mul_f32 v[82:83], v[82:83], v[168:169] op_sel_hi:[1,0]
	v_mul_f32_e32 v186, 0xbfb8aa3b, v92
	v_mul_f32_e32 v187, 0xbfb8aa3b, v93
	v_mul_f32_e32 v188, 0xbfb8aa3b, v94
	v_mul_f32_e32 v189, 0xbfb8aa3b, v95
	v_mul_f32_e32 v190, 0xbfb8aa3b, v84
	v_mul_f32_e32 v191, 0xbfb8aa3b, v85
	v_mul_f32_e32 v192, 0xbfb8aa3b, v86
	v_mul_f32_e32 v193, 0xbfb8aa3b, v87
	v_exp_f32_e32 v186, v186
	v_exp_f32_e32 v187, v187
	v_exp_f32_e32 v188, v188
	v_exp_f32_e32 v189, v189
	v_exp_f32_e32 v190, v190
	v_exp_f32_e32 v191, v191
	v_exp_f32_e32 v192, v192
	v_exp_f32_e32 v193, v193
	v_add_f32_e32 v186, 1.0, v186
	v_add_f32_e32 v187, 1.0, v187
	v_add_f32_e32 v188, 1.0, v188
	v_add_f32_e32 v189, 1.0, v189
	v_add_f32_e32 v190, 1.0, v190
	v_add_f32_e32 v191, 1.0, v191
	v_add_f32_e32 v192, 1.0, v192
	v_add_f32_e32 v193, 1.0, v193
	v_rcp_f32_e32 v186, v186
	v_rcp_f32_e32 v187, v187
	v_rcp_f32_e32 v188, v188
	v_rcp_f32_e32 v189, v189
	v_rcp_f32_e32 v190, v190
	v_rcp_f32_e32 v191, v191
	v_rcp_f32_e32 v192, v192
	v_rcp_f32_e32 v193, v193
	v_pk_mul_f32 v[92:93], v[92:93], v[186:187]
	v_pk_mul_f32 v[94:95], v[94:95], v[188:189]
	v_pk_mul_f32 v[84:85], v[84:85], v[190:191]
	v_pk_mul_f32 v[86:87], v[86:87], v[192:193]
	v_pk_mul_f32 v[92:93], v[88:89], v[92:93]
	v_pk_mul_f32 v[94:95], v[90:91], v[94:95]
	v_pk_mul_f32 v[84:85], v[80:81], v[84:85]
	v_pk_mul_f32 v[86:87], v[82:83], v[86:87]
	v_cvt_pk_bf16_f32 v80, v92, v93
	v_cvt_pk_bf16_f32 v81, v94, v95
	v_cvt_pk_bf16_f32 v82, v84, v85
	v_cvt_pk_bf16_f32 v83, v86, v87
	global_store_dwordx4 v206, v[80:83], s[82:83]
	s_waitcnt lgkmcnt(4)
	v_pk_mul_f32 v[76:77], v[76:77], v[170:171] op_sel_hi:[1,0]
	v_pk_mul_f32 v[78:79], v[78:79], v[170:171] op_sel_hi:[1,0]
	v_pk_mul_f32 v[68:69], v[68:69], v[170:171] op_sel_hi:[1,0]
	v_pk_mul_f32 v[70:71], v[70:71], v[170:171] op_sel_hi:[1,0]
	v_pk_mul_f32 v[72:73], v[72:73], v[170:171] op_sel_hi:[1,0]
	v_pk_mul_f32 v[74:75], v[74:75], v[170:171] op_sel_hi:[1,0]
	v_pk_mul_f32 v[64:65], v[64:65], v[170:171] op_sel_hi:[1,0]
	v_pk_mul_f32 v[66:67], v[66:67], v[170:171] op_sel_hi:[1,0]
	v_mul_f32_e32 v194, 0xbfb8aa3b, v76
	v_mul_f32_e32 v195, 0xbfb8aa3b, v77
	v_mul_f32_e32 v196, 0xbfb8aa3b, v78
	v_mul_f32_e32 v197, 0xbfb8aa3b, v79
	v_mul_f32_e32 v198, 0xbfb8aa3b, v68
	v_mul_f32_e32 v199, 0xbfb8aa3b, v69
	v_mul_f32_e32 v200, 0xbfb8aa3b, v70
	v_mul_f32_e32 v201, 0xbfb8aa3b, v71
	v_exp_f32_e32 v194, v194
	v_exp_f32_e32 v195, v195
	v_exp_f32_e32 v196, v196
	v_exp_f32_e32 v197, v197
	v_exp_f32_e32 v198, v198
	v_exp_f32_e32 v199, v199
	v_exp_f32_e32 v200, v200
	v_exp_f32_e32 v201, v201
	v_add_f32_e32 v194, 1.0, v194
	v_add_f32_e32 v195, 1.0, v195
	v_add_f32_e32 v196, 1.0, v196
	v_add_f32_e32 v197, 1.0, v197
	v_add_f32_e32 v198, 1.0, v198
	v_add_f32_e32 v199, 1.0, v199
	v_add_f32_e32 v200, 1.0, v200
	v_add_f32_e32 v201, 1.0, v201
	v_rcp_f32_e32 v194, v194
	v_rcp_f32_e32 v195, v195
	v_rcp_f32_e32 v196, v196
	v_rcp_f32_e32 v197, v197
	v_rcp_f32_e32 v198, v198
	v_rcp_f32_e32 v199, v199
	v_rcp_f32_e32 v200, v200
	v_rcp_f32_e32 v201, v201
	v_pk_mul_f32 v[76:77], v[76:77], v[194:195]
	v_pk_mul_f32 v[78:79], v[78:79], v[196:197]
	v_pk_mul_f32 v[68:69], v[68:69], v[198:199]
	v_pk_mul_f32 v[70:71], v[70:71], v[200:201]
	v_pk_mul_f32 v[76:77], v[72:73], v[76:77]
	v_pk_mul_f32 v[78:79], v[74:75], v[78:79]
	v_pk_mul_f32 v[68:69], v[64:65], v[68:69]
	v_pk_mul_f32 v[70:71], v[66:67], v[70:71]
	v_cvt_pk_bf16_f32 v64, v76, v77
	v_cvt_pk_bf16_f32 v65, v78, v79
	v_cvt_pk_bf16_f32 v66, v68, v69
	v_cvt_pk_bf16_f32 v67, v70, v71
	global_store_dwordx4 v207, v[64:67], s[82:83]
	s_waitcnt lgkmcnt(3)
	v_pk_mul_f32 v[60:61], v[60:61], v[172:173] op_sel_hi:[1,0]
	v_pk_mul_f32 v[62:63], v[62:63], v[172:173] op_sel_hi:[1,0]
	v_pk_mul_f32 v[52:53], v[52:53], v[172:173] op_sel_hi:[1,0]
	v_pk_mul_f32 v[54:55], v[54:55], v[172:173] op_sel_hi:[1,0]
	v_pk_mul_f32 v[56:57], v[56:57], v[172:173] op_sel_hi:[1,0]
	v_pk_mul_f32 v[58:59], v[58:59], v[172:173] op_sel_hi:[1,0]
	v_pk_mul_f32 v[48:49], v[48:49], v[172:173] op_sel_hi:[1,0]
	v_pk_mul_f32 v[50:51], v[50:51], v[172:173] op_sel_hi:[1,0]
	v_mul_f32_e32 v186, 0xbfb8aa3b, v60
	v_mul_f32_e32 v187, 0xbfb8aa3b, v61
	v_mul_f32_e32 v188, 0xbfb8aa3b, v62
	v_mul_f32_e32 v189, 0xbfb8aa3b, v63
	v_mul_f32_e32 v190, 0xbfb8aa3b, v52
	v_mul_f32_e32 v191, 0xbfb8aa3b, v53
	v_mul_f32_e32 v192, 0xbfb8aa3b, v54
	v_mul_f32_e32 v193, 0xbfb8aa3b, v55
	v_exp_f32_e32 v186, v186
	v_exp_f32_e32 v187, v187
	v_exp_f32_e32 v188, v188
	v_exp_f32_e32 v189, v189
	v_exp_f32_e32 v190, v190
	v_exp_f32_e32 v191, v191
	v_exp_f32_e32 v192, v192
	v_exp_f32_e32 v193, v193
	v_add_f32_e32 v186, 1.0, v186
	v_add_f32_e32 v187, 1.0, v187
	v_add_f32_e32 v188, 1.0, v188
	v_add_f32_e32 v189, 1.0, v189
	v_add_f32_e32 v190, 1.0, v190
	v_add_f32_e32 v191, 1.0, v191
	v_add_f32_e32 v192, 1.0, v192
	v_add_f32_e32 v193, 1.0, v193
	v_rcp_f32_e32 v186, v186
	v_rcp_f32_e32 v187, v187
	v_rcp_f32_e32 v188, v188
	v_rcp_f32_e32 v189, v189
	v_rcp_f32_e32 v190, v190
	v_rcp_f32_e32 v191, v191
	v_rcp_f32_e32 v192, v192
	v_rcp_f32_e32 v193, v193
	v_pk_mul_f32 v[60:61], v[60:61], v[186:187]
	v_pk_mul_f32 v[62:63], v[62:63], v[188:189]
	v_pk_mul_f32 v[52:53], v[52:53], v[190:191]
	v_pk_mul_f32 v[54:55], v[54:55], v[192:193]
	v_pk_mul_f32 v[60:61], v[56:57], v[60:61]
	v_pk_mul_f32 v[62:63], v[58:59], v[62:63]
	v_pk_mul_f32 v[52:53], v[48:49], v[52:53]
	v_pk_mul_f32 v[54:55], v[50:51], v[54:55]
	v_cvt_pk_bf16_f32 v48, v60, v61
	v_cvt_pk_bf16_f32 v49, v62, v63
	v_cvt_pk_bf16_f32 v50, v52, v53
	v_cvt_pk_bf16_f32 v51, v54, v55
	global_store_dwordx4 v208, v[48:51], s[82:83]
	s_waitcnt lgkmcnt(2)
	v_pk_mul_f32 v[44:45], v[44:45], v[174:175] op_sel_hi:[1,0]
	v_pk_mul_f32 v[46:47], v[46:47], v[174:175] op_sel_hi:[1,0]
	v_pk_mul_f32 v[36:37], v[36:37], v[174:175] op_sel_hi:[1,0]
	v_pk_mul_f32 v[38:39], v[38:39], v[174:175] op_sel_hi:[1,0]
	v_pk_mul_f32 v[40:41], v[40:41], v[174:175] op_sel_hi:[1,0]
	v_pk_mul_f32 v[42:43], v[42:43], v[174:175] op_sel_hi:[1,0]
	v_pk_mul_f32 v[32:33], v[32:33], v[174:175] op_sel_hi:[1,0]
	v_pk_mul_f32 v[34:35], v[34:35], v[174:175] op_sel_hi:[1,0]
	v_mul_f32_e32 v194, 0xbfb8aa3b, v44
	v_mul_f32_e32 v195, 0xbfb8aa3b, v45
	v_mul_f32_e32 v196, 0xbfb8aa3b, v46
	v_mul_f32_e32 v197, 0xbfb8aa3b, v47
	v_mul_f32_e32 v198, 0xbfb8aa3b, v36
	v_mul_f32_e32 v199, 0xbfb8aa3b, v37
	v_mul_f32_e32 v200, 0xbfb8aa3b, v38
	v_mul_f32_e32 v201, 0xbfb8aa3b, v39
	v_exp_f32_e32 v194, v194
	v_exp_f32_e32 v195, v195
	v_exp_f32_e32 v196, v196
	v_exp_f32_e32 v197, v197
	v_exp_f32_e32 v198, v198
	v_exp_f32_e32 v199, v199
	v_exp_f32_e32 v200, v200
	v_exp_f32_e32 v201, v201
	v_add_f32_e32 v194, 1.0, v194
	v_add_f32_e32 v195, 1.0, v195
	v_add_f32_e32 v196, 1.0, v196
	v_add_f32_e32 v197, 1.0, v197
	v_add_f32_e32 v198, 1.0, v198
	v_add_f32_e32 v199, 1.0, v199
	v_add_f32_e32 v200, 1.0, v200
	v_add_f32_e32 v201, 1.0, v201
	v_rcp_f32_e32 v194, v194
	v_rcp_f32_e32 v195, v195
	v_rcp_f32_e32 v196, v196
	v_rcp_f32_e32 v197, v197
	v_rcp_f32_e32 v198, v198
	v_rcp_f32_e32 v199, v199
	v_rcp_f32_e32 v200, v200
	v_rcp_f32_e32 v201, v201
	v_pk_mul_f32 v[44:45], v[44:45], v[194:195]
	v_pk_mul_f32 v[46:47], v[46:47], v[196:197]
	v_pk_mul_f32 v[36:37], v[36:37], v[198:199]
	v_pk_mul_f32 v[38:39], v[38:39], v[200:201]
	v_pk_mul_f32 v[44:45], v[40:41], v[44:45]
	v_pk_mul_f32 v[46:47], v[42:43], v[46:47]
	v_pk_mul_f32 v[36:37], v[32:33], v[36:37]
	v_pk_mul_f32 v[38:39], v[34:35], v[38:39]
	v_cvt_pk_bf16_f32 v32, v44, v45
	v_cvt_pk_bf16_f32 v33, v46, v47
	v_cvt_pk_bf16_f32 v34, v36, v37
	v_cvt_pk_bf16_f32 v35, v38, v39
	global_store_dwordx4 v209, v[32:35], s[82:83]
	s_waitcnt lgkmcnt(1)
	v_pk_mul_f32 v[28:29], v[28:29], v[176:177] op_sel_hi:[1,0]
	v_pk_mul_f32 v[30:31], v[30:31], v[176:177] op_sel_hi:[1,0]
	v_pk_mul_f32 v[20:21], v[20:21], v[176:177] op_sel_hi:[1,0]
	v_pk_mul_f32 v[22:23], v[22:23], v[176:177] op_sel_hi:[1,0]
	v_pk_mul_f32 v[24:25], v[24:25], v[176:177] op_sel_hi:[1,0]
	v_pk_mul_f32 v[26:27], v[26:27], v[176:177] op_sel_hi:[1,0]
	v_pk_mul_f32 v[16:17], v[16:17], v[176:177] op_sel_hi:[1,0]
	v_pk_mul_f32 v[18:19], v[18:19], v[176:177] op_sel_hi:[1,0]
	v_mul_f32_e32 v186, 0xbfb8aa3b, v28
	v_mul_f32_e32 v187, 0xbfb8aa3b, v29
	v_mul_f32_e32 v188, 0xbfb8aa3b, v30
	v_mul_f32_e32 v189, 0xbfb8aa3b, v31
	v_mul_f32_e32 v190, 0xbfb8aa3b, v20
	v_mul_f32_e32 v191, 0xbfb8aa3b, v21
	v_mul_f32_e32 v192, 0xbfb8aa3b, v22
	v_mul_f32_e32 v193, 0xbfb8aa3b, v23
	v_exp_f32_e32 v186, v186
	v_exp_f32_e32 v187, v187
	v_exp_f32_e32 v188, v188
	v_exp_f32_e32 v189, v189
	v_exp_f32_e32 v190, v190
	v_exp_f32_e32 v191, v191
	v_exp_f32_e32 v192, v192
	v_exp_f32_e32 v193, v193
	v_add_f32_e32 v186, 1.0, v186
	v_add_f32_e32 v187, 1.0, v187
	v_add_f32_e32 v188, 1.0, v188
	v_add_f32_e32 v189, 1.0, v189
	v_add_f32_e32 v190, 1.0, v190
	v_add_f32_e32 v191, 1.0, v191
	v_add_f32_e32 v192, 1.0, v192
	v_add_f32_e32 v193, 1.0, v193
	v_rcp_f32_e32 v186, v186
	v_rcp_f32_e32 v187, v187
	v_rcp_f32_e32 v188, v188
	v_rcp_f32_e32 v189, v189
	v_rcp_f32_e32 v190, v190
	v_rcp_f32_e32 v191, v191
	v_rcp_f32_e32 v192, v192
	v_rcp_f32_e32 v193, v193
	v_pk_mul_f32 v[28:29], v[28:29], v[186:187]
	v_pk_mul_f32 v[30:31], v[30:31], v[188:189]
	v_pk_mul_f32 v[20:21], v[20:21], v[190:191]
	v_pk_mul_f32 v[22:23], v[22:23], v[192:193]
	v_pk_mul_f32 v[28:29], v[24:25], v[28:29]
	v_pk_mul_f32 v[30:31], v[26:27], v[30:31]
	v_pk_mul_f32 v[20:21], v[16:17], v[20:21]
	v_pk_mul_f32 v[22:23], v[18:19], v[22:23]
	v_cvt_pk_bf16_f32 v16, v28, v29
	v_cvt_pk_bf16_f32 v17, v30, v31
	v_cvt_pk_bf16_f32 v18, v20, v21
	v_cvt_pk_bf16_f32 v19, v22, v23
	global_store_dwordx4 v210, v[16:19], s[82:83]
	s_waitcnt lgkmcnt(0)
	v_pk_mul_f32 v[12:13], v[12:13], v[178:179] op_sel_hi:[1,0]
	v_pk_mul_f32 v[14:15], v[14:15], v[178:179] op_sel_hi:[1,0]
	v_pk_mul_f32 v[4:5], v[4:5], v[178:179] op_sel_hi:[1,0]
	v_pk_mul_f32 v[6:7], v[6:7], v[178:179] op_sel_hi:[1,0]
	v_pk_mul_f32 v[8:9], v[8:9], v[178:179] op_sel_hi:[1,0]
	v_pk_mul_f32 v[10:11], v[10:11], v[178:179] op_sel_hi:[1,0]
	v_pk_mul_f32 v[0:1], v[0:1], v[178:179] op_sel_hi:[1,0]
	v_pk_mul_f32 v[2:3], v[2:3], v[178:179] op_sel_hi:[1,0]
	v_mul_f32_e32 v194, 0xbfb8aa3b, v12
	v_mul_f32_e32 v195, 0xbfb8aa3b, v13
	v_mul_f32_e32 v196, 0xbfb8aa3b, v14
	v_mul_f32_e32 v197, 0xbfb8aa3b, v15
	v_mul_f32_e32 v198, 0xbfb8aa3b, v4
	v_mul_f32_e32 v199, 0xbfb8aa3b, v5
	v_mul_f32_e32 v200, 0xbfb8aa3b, v6
	v_mul_f32_e32 v201, 0xbfb8aa3b, v7
	v_exp_f32_e32 v194, v194
	v_exp_f32_e32 v195, v195
	v_exp_f32_e32 v196, v196
	v_exp_f32_e32 v197, v197
	v_exp_f32_e32 v198, v198
	v_exp_f32_e32 v199, v199
	v_exp_f32_e32 v200, v200
	v_exp_f32_e32 v201, v201
	v_add_f32_e32 v194, 1.0, v194
	v_add_f32_e32 v195, 1.0, v195
	v_add_f32_e32 v196, 1.0, v196
	v_add_f32_e32 v197, 1.0, v197
	v_add_f32_e32 v198, 1.0, v198
	v_add_f32_e32 v199, 1.0, v199
	v_add_f32_e32 v200, 1.0, v200
	v_add_f32_e32 v201, 1.0, v201
	v_rcp_f32_e32 v194, v194
	v_rcp_f32_e32 v195, v195
	v_rcp_f32_e32 v196, v196
	v_rcp_f32_e32 v197, v197
	v_rcp_f32_e32 v198, v198
	v_rcp_f32_e32 v199, v199
	v_rcp_f32_e32 v200, v200
	v_rcp_f32_e32 v201, v201
	v_pk_mul_f32 v[12:13], v[12:13], v[194:195]
	v_pk_mul_f32 v[14:15], v[14:15], v[196:197]
	v_pk_mul_f32 v[4:5], v[4:5], v[198:199]
	v_pk_mul_f32 v[6:7], v[6:7], v[200:201]
	v_pk_mul_f32 v[12:13], v[8:9], v[12:13]
	v_pk_mul_f32 v[14:15], v[10:11], v[14:15]
	v_pk_mul_f32 v[4:5], v[0:1], v[4:5]
	v_pk_mul_f32 v[6:7], v[2:3], v[6:7]
	v_cvt_pk_bf16_f32 v0, v12, v13
	v_cvt_pk_bf16_f32 v1, v14, v15
	v_cvt_pk_bf16_f32 v2, v4, v5
	v_cvt_pk_bf16_f32 v3, v6, v7
	global_store_dwordx4 v211, v[0:3], s[82:83]
	s_mov_b64 s[4:5], -1
	s_cbranch_vccnz .LBB0_912
	s_and_b64 vcc, exec, s[0:1]
	s_cbranch_vccnz .LBB0_911
	s_barrier
	s_branch .LBB0_911
